# prologue weight-transpose loop: the per-item job search resumes from the previous item's job (monotonic item index) instead of rescanning all 22 jobs
# baseline (speedup 1.0000x reference)
; #define LAS __attribute__((address_space(3)))
; #define LDS_WAIT() asm volatile("s_waitcnt lgkmcnt(0)" ::: "memory")
; __device__ __forceinline__ unsigned pk2(float lo, float hi) { return f2bf(lo) | (f2bf(hi) << 16); }
; __device__ __forceinline__ void transpose_item(const Job& jb, LAS float* scr, int item, int lane) {
;     ...
;     for (int i = 0; i < 8; ++i) { const int kk = 8 * i + (lane >> 3), c4 = 4 * (lane & 7); const float g = jb.gain ? jb.gain[k0 + kk] : 1.0f;
;         const f32x4 v = *(const f32x4*)(jb.src + (size_t)(k0 + kk) * N + n0 + c4); LAS float* d = scr + kk * 33 + c4;
;         d[0] = v.x * g; d[1] = v.y * g; d[2] = v.z * g; d[3] = v.w * g; }
;     LDS_WAIT(); asm volatile("" ::: "memory");
;     const int c = lane & 7;
; #pragma unroll
;     for (int j = 0; j < 4; ++j) { const int n = (lane >> 3) + 8 * j; const LAS float* s = scr + (8 * c) * 33 + n;
;         v4u o; o.x = pk2(s[0 * 33], s[1 * 33]); o.y = pk2(s[2 * 33], s[3 * 33]); o.z = pk2(s[4 * 33], s[5 * 33]); o.w = pk2(s[6 * 33], s[7 * 33]);
; __global__ void __launch_bounds__(NWAVES * 64, 2) mk_fwd(Args args) {
;     ...
;     const int gw = bx * NWAVES + wave, NGW = G * NWAVES;
;     unsigned char* ws = args.ws;
;     float* KSUM = (float*)(ws + WS_KSUM); float* SS = (float*)(ws + WS_SS);
;     bf16* W = (bf16*)(ws + WS_W); bf16* MEMN = (bf16*)(ws + WS_MEMN); bf16* XKP = (bf16*)(ws + WS_XKP); bf16* XVP = (bf16*)(ws + WS_XVP);
;     bf16* XB = (bf16*)(ws + WS_XB);
;     const float* x_in = args.in[0]; float* OUT = args.out;
;     if (tid < 2) ((LAS unsigned*)(lds + LDS_BARST_OFF))[tid] = 0u;
;     __syncthreads();
;     const XcdBarrier bar = xcd_barrier_post((unsigned*)(ws + WS_BAR), (volatile LAS unsigned*)(lds + LDS_BARST_OFF));
;     for (int prep = 0; prep < NREP(10); ++prep) {
;         LAS float* scr = (LAS float*)(lds + wave * 16384);
;         for (int it = gw; it < N_JOB_ITEMS; it += NGW) {
;             int r = it, j = 0; Job jb;
;             for (;;) { jb = get_job(j, args, W); const int cnt = (jb.K / 64) * (jb.N / 32); if (r < cnt || j >= 21) break; r -= cnt; ++j; }
.LBB0_5:
	s_or_b64 exec, exec, s[4:5]
	s_lshr_b32 s3, s3, 6
	s_lshl_b32 s4, s2, 3
	v_writelane_b32 v250, s4, 8
	s_add_i32 s4, s3, s4
	s_lshl_b32 s80, s72, 3
	s_add_u32 s94, s70, 0x400000
	s_addc_u32 s96, s71, 0
	s_add_u32 s6, s70, 0x4c80000
	s_addc_u32 s7, s71, 0
	s_add_u32 s82, s70, 0x4a80000
	s_addc_u32 s83, s71, 0
	s_add_u32 s84, s70, 0x4600000
	v_writelane_b32 v250, s6, 9
	s_addc_u32 s85, s71, 0
	s_load_dwordx16 s[52:67], s[0:1], 0x0
	s_load_dwordx16 s[36:51], s[0:1], 0x40
	v_writelane_b32 v250, s7, 10
	s_add_u32 s6, s70, 0x5080000
	s_addc_u32 s7, s71, 0
	v_writelane_b32 v250, s6, 11
	s_add_u32 s5, s70, 0x5480000
	s_load_dwordx16 s[16:31], s[0:1], 0x80
	v_writelane_b32 v250, s7, 12
	v_writelane_b32 v250, s5, 13
	s_addc_u32 s5, s71, 0
	v_writelane_b32 v250, s5, 14
	s_add_u32 s5, s70, 0x5280000
	v_writelane_b32 v250, s5, 15
	s_addc_u32 s5, s71, 0
	s_add_u32 s81, s70, 0x3b00000
	v_writelane_b32 v250, s5, 16
	s_addc_u32 s5, s71, 0
	v_writelane_b32 v250, s5, 17
	s_add_u32 s5, s70, 0x2500000
	v_writelane_b32 v250, s5, 18
	s_addc_u32 s5, s71, 0
	s_add_u32 s95, s70, 0x1a00000
	s_addc_u32 s34, s71, 0
	s_add_u32 s76, s70, 0x5880000
	s_addc_u32 s77, s71, 0
	v_and_b32_e32 v11, 63, v204
	s_cmpk_gt_i32 s4, 0x567f
	v_lshlrev_b32_e32 v1, 2, v204
	v_writelane_b32 v250, s5, 19
	s_cbranch_scc1 .LBB0_82
	s_lshl_b32 s0, s3, 14
	s_add_i32 s0, s0, 0
	v_lshrrev_b32_e32 v2, 3, v11
	v_and_b32_e32 v4, 28, v1
	v_lshlrev_b32_e32 v3, 3, v204
	v_lshl_add_u32 v9, v4, 2, s0
	v_mul_u32_u24_e32 v10, 0x84, v2
	v_and_b32_e32 v8, 56, v3
	s_waitcnt lgkmcnt(0)
	s_add_u32 s6, s64, 0x1000
	v_mov_b32_e32 v5, 0
	v_mul_u32_u24_e32 v3, 0x84, v8
	v_lshlrev_b32_e32 v6, 2, v2
	v_add_u32_e32 v23, v9, v10
	s_addc_u32 s7, s65, 0
	v_or_b32_e32 v13, 8, v2
	v_or_b32_e32 v16, 16, v2
	v_or_b32_e32 v17, 24, v2
	v_or_b32_e32 v18, 32, v2
	v_or_b32_e32 v19, 40, v2
	v_or_b32_e32 v20, 48, v2
	v_or_b32_e32 v21, 56, v2
	v_add3_u32 v22, s0, v3, v6
	v_mov_b32_e32 v3, v5
	v_lshlrev_b32_e32 v6, 2, v4
	v_mov_b32_e32 v7, v5
	v_add_u32_e32 v24, 0x420, v23
	v_add_u32_e32 v25, 0x428, v23
	s_movk_i32 s5, 0x7fff
	s_mov_b32 s35, 0xffff0000
	v_lshlrev_b32_e32 v4, 1, v8
	v_add_u32_e32 v26, 0x840, v23
	v_add_u32_e32 v27, 0x848, v23
	s_mov_b32 s97, s4
	s_mov_b32 s99, -9
	s_sub_i32 s98, s4, s80
	s_branch .LBB0_8

; __global__ void __launch_bounds__(NWAVES * 64, 2) mk_fwd(Args args) {
;     ...
;         for (int it = gw; it < N_JOB_ITEMS; it += NGW) {
;             int r = it, j = 0; Job jb;
;             for (;;) { jb = get_job(j, args, W); const int cnt = (jb.K / 64) * (jb.N / 32); if (r < cnt || j >= 21) break; r -= cnt; ++j; }
.LBB0_8:
	s_mov_b32 s75, s99
	s_add_i32 s33, s98, s80
	s_branch .LBB0_10

; __device__ __forceinline__ void transpose_item(const Job& jb, LAS float* scr, int item, int lane) {
;     const int K = jb.K, N = jb.N; const int nblk = N / 32, kb = item / nblk, nb = item % nblk, k0 = 64 * kb, n0 = 32 * nb;
;     int r0 = n0; if (jb.mode) r0 = 256 * (n0 / 128) + (n0 % 128) + (jb.mode == 2 ? 128 : 0);
; __global__ void __launch_bounds__(NWAVES * 64, 2) mk_fwd(Args args) {
;     ...
;             int r = it, j = 0; Job jb;
;             for (;;) { jb = get_job(j, args, W); const int cnt = (jb.K / 64) * (jb.N / 32); if (r < cnt || j >= 21) break; r -= cnt; ++j; }
.LBB0_61:
	s_mov_b32 s98, s15
	s_add_i32 s99, s75, -1
	v_cvt_f32_u32_e32 v8, s3
	s_sub_i32 s79, 0, s3
	s_xor_b64 s[86:87], s[12:13], -1
	s_abs_i32 s75, s15
	v_rcp_iflag_f32_e32 v8, v8
	s_ashr_i32 s33, s15, 31
	v_mul_f32_e32 v8, 0x4f7ffffe, v8
	v_cvt_u32_f32_e32 v8, v8
	s_nop 0
	v_readfirstlane_b32 s12, v8
	s_mul_i32 s79, s79, s12
	s_mul_hi_u32 s13, s12, s79
	s_add_i32 s12, s12, s13
	s_mul_hi_u32 s12, s75, s12
	s_mul_i32 s13, s12, s3
	s_sub_i32 s13, s75, s13
	s_add_i32 s79, s12, 1
	s_sub_i32 s75, s13, s3
	s_cmp_ge_u32 s13, s3
	s_cselect_b32 s12, s79, s12
	s_cselect_b32 s13, s75, s13
	s_add_i32 s75, s12, 1
	s_cmp_ge_u32 s13, s3
	s_cselect_b32 s12, s75, s12
	s_xor_b32 s12, s12, s33
	s_sub_i32 s12, s12, s33
	s_mul_i32 s3, s12, s3
	s_sub_i32 s3, s15, s3
	s_lshl_b32 s88, s3, 5
	s_andn2_b64 vcc, exec, s[86:87]
	s_mov_b32 s15, s88
	s_cbranch_vccnz .LBB0_63
	s_bfe_i32 s13, s3, 0x80000
	s_bfe_u32 s13, s13, 0x2000d
	s_add_i32 s3, s3, s13
	s_bfe_u32 s13, s88, 0x70018
	s_add_i32 s13, s88, s13
	s_bfe_i32 s3, s3, 0x80000
	s_and_b32 s13, s13, 0xff80
	s_sext_i32_i16 s3, s3
	s_sub_i32 s13, s88, s13
	s_lshl_b32 s3, s3, 6
	s_sext_i32_i16 s13, s13
	s_and_b32 s3, s3, 0xffffff00
	s_add_i32 s13, s78, s13
	s_add_i32 s15, s13, s3
